# baseline (speedup 1.0000x reference)
; template <bool FOX>
; __device__ __forceinline__ void attn_pair(const Params& p, int it, char* smem, const int wv) {
;     ...
;     const float* Fl = (const float*)(p.ws + OFF_F) + tok0 * 16 + h;
;     const float bf = p.b_f[h];
;     const int n = (qb_ + 1) * 256;
;     const int s0 = tid * 8;
;     float run = 0.f;
;     #pragma unroll 1
;     for (int j = 0; j < 8; ++j) {
;       const int s_ = s0 + j;
;       float lf = 0.f;
;       if (s_ < n) { const float* fp = Fl + (long)s_ * 16;
;         lf = log_sigmoid_acc(((fp[0] + fp[(long)NTOK * 16]) + (fp[(long)2 * NTOK * 16] + fp[(long)3 * NTOK * 16])) + bf); }
.LBB0_720:
	s_or_b64 exec, exec, s[0:1]
	v_add_u32_e32 v0, 0, v0
	s_waitcnt lgkmcnt(0)
	s_barrier
	ds_read_b32 v0, v0
	s_mov_b64 s[0:1], -1
	s_waitcnt lgkmcnt(0)
	v_readfirstlane_b32 s4, v0
	s_cmpk_gt_i32 s4, 0x3ff
	s_cbranch_scc1 .LBB0_715
	s_and_b32 s20, s4, 15
	s_lshl_b32 s0, s20, 2
	v_mov_b32_e32 v0, s0
	s_waitcnt vmcnt(14)
	v_mbcnt_lo_u32_b32 v6, -1, 0
	v_mbcnt_hi_u32_b32 v6, -1, v6
	global_load_dword v7, v0, s[72:73]
	s_ashr_i32 s21, s4, 6
	s_lshl_b32 s1, s4, 8
	s_and_b32 s38, s1, 0x3000
	s_sub_i32 s14, 16, s21
	s_lshl_b32 s1, s38, 6
	s_lshl_b32 s33, s14, 8
	v_or_b32_e32 v0, s67, v6
	s_add_u32 s0, s96, s0
	v_lshlrev_b32_e32 v2, 3, v0
	s_addc_u32 s4, s97, 0
	v_ashrrev_i32_e32 v3, 31, v2
	s_add_u32 s0, s0, s1
	v_lshlrev_b64 v[4:5], 6, v[2:3]
	s_addc_u32 s1, s4, 0
	v_lshl_add_u32 v0, v0, 5, s23
	v_lshl_add_u64 v[4:5], s[0:1], 0, v[4:5]
	v_mov_b32_e32 v3, 0
	s_mov_b64 s[0:1], 0
	s_waitcnt vmcnt(14)
	v_mov_b32_e32 v8, v0
	v_lshl_add_u64 v[10:11], v[4:5], 0, s[0:1]
	v_add_co_u32_e32 v12, vcc, 0x1a800000, v10
	s_nop 1
	v_addc_co_u32_e32 v13, vcc, 0, v11, vcc
	v_add_co_u32_e32 v14, vcc, 0x1a900000, v10
	s_nop 1
	v_addc_co_u32_e32 v15, vcc, 0, v11, vcc
	v_add_co_u32_e32 v16, vcc, 0x1aa00000, v10
	s_nop 1
	v_addc_co_u32_e32 v17, vcc, 0, v11, vcc
	v_add_co_u32_e32 v10, vcc, 0x1ab00000, v10
	s_nop 1
	v_addc_co_u32_e32 v11, vcc, 0, v11, vcc
	s_nop 0
	global_load_dword v222, v[12:13], off
	s_nop 0
	global_load_dword v224, v[14:15], off
	s_nop 0
	global_load_dword v223, v[16:17], off
	s_nop 0
	global_load_dword v225, v[10:11], off
	s_add_u32 s0, s0, 64
	s_addc_u32 s1, s1, 0
	v_lshl_add_u64 v[10:11], v[4:5], 0, s[0:1]
	v_add_co_u32_e32 v12, vcc, 0x1a800000, v10
	s_nop 1
	v_addc_co_u32_e32 v13, vcc, 0, v11, vcc
	v_add_co_u32_e32 v14, vcc, 0x1a900000, v10
	s_nop 1
	v_addc_co_u32_e32 v15, vcc, 0, v11, vcc
	v_add_co_u32_e32 v16, vcc, 0x1aa00000, v10
	s_nop 1
	v_addc_co_u32_e32 v17, vcc, 0, v11, vcc
	v_add_co_u32_e32 v10, vcc, 0x1ab00000, v10
	s_nop 1
	v_addc_co_u32_e32 v11, vcc, 0, v11, vcc
	s_nop 0
	global_load_dword v226, v[12:13], off
	s_nop 0
	global_load_dword v228, v[14:15], off
	s_nop 0
	global_load_dword v227, v[16:17], off
	s_nop 0
	global_load_dword v229, v[10:11], off
	s_add_u32 s0, s0, 64
	s_addc_u32 s1, s1, 0
	v_lshl_add_u64 v[10:11], v[4:5], 0, s[0:1]
	v_add_co_u32_e32 v12, vcc, 0x1a800000, v10
	s_nop 1
	v_addc_co_u32_e32 v13, vcc, 0, v11, vcc
	v_add_co_u32_e32 v14, vcc, 0x1a900000, v10
	s_nop 1
	v_addc_co_u32_e32 v15, vcc, 0, v11, vcc
	v_add_co_u32_e32 v16, vcc, 0x1aa00000, v10
	s_nop 1
	v_addc_co_u32_e32 v17, vcc, 0, v11, vcc
	v_add_co_u32_e32 v10, vcc, 0x1ab00000, v10
	s_nop 1
	v_addc_co_u32_e32 v11, vcc, 0, v11, vcc
	s_nop 0
	global_load_dword v230, v[12:13], off
	s_nop 0
	global_load_dword v232, v[14:15], off
	s_nop 0
	global_load_dword v231, v[16:17], off
	s_nop 0
	global_load_dword v233, v[10:11], off
	s_add_u32 s0, s0, 64
	s_addc_u32 s1, s1, 0
	v_lshl_add_u64 v[10:11], v[4:5], 0, s[0:1]
	v_add_co_u32_e32 v12, vcc, 0x1a800000, v10
	s_nop 1
	v_addc_co_u32_e32 v13, vcc, 0, v11, vcc
	v_add_co_u32_e32 v14, vcc, 0x1a900000, v10
	s_nop 1
	v_addc_co_u32_e32 v15, vcc, 0, v11, vcc
	v_add_co_u32_e32 v16, vcc, 0x1aa00000, v10
	s_nop 1
	v_addc_co_u32_e32 v17, vcc, 0, v11, vcc
	v_add_co_u32_e32 v10, vcc, 0x1ab00000, v10
	s_nop 1
	v_addc_co_u32_e32 v11, vcc, 0, v11, vcc
	s_nop 0
	global_load_dword v234, v[12:13], off
	s_nop 0
	global_load_dword v236, v[14:15], off
	s_nop 0
	global_load_dword v235, v[16:17], off
	s_nop 0
	global_load_dword v237, v[10:11], off
	s_add_u32 s0, s0, 64
	s_addc_u32 s1, s1, 0
	v_lshl_add_u64 v[10:11], v[4:5], 0, s[0:1]
	v_add_co_u32_e32 v12, vcc, 0x1a800000, v10
	s_nop 1
	v_addc_co_u32_e32 v13, vcc, 0, v11, vcc
	v_add_co_u32_e32 v14, vcc, 0x1a900000, v10
	s_nop 1
	v_addc_co_u32_e32 v15, vcc, 0, v11, vcc
	v_add_co_u32_e32 v16, vcc, 0x1aa00000, v10
	s_nop 1
	v_addc_co_u32_e32 v17, vcc, 0, v11, vcc
	v_add_co_u32_e32 v10, vcc, 0x1ab00000, v10
	s_nop 1
	v_addc_co_u32_e32 v11, vcc, 0, v11, vcc
	s_nop 0
	global_load_dword v238, v[12:13], off
	s_nop 0
	global_load_dword v240, v[14:15], off
	s_nop 0
	global_load_dword v239, v[16:17], off
	s_nop 0
	global_load_dword v241, v[10:11], off
	s_add_u32 s0, s0, 64
	s_addc_u32 s1, s1, 0
	v_lshl_add_u64 v[10:11], v[4:5], 0, s[0:1]
	v_add_co_u32_e32 v12, vcc, 0x1a800000, v10
	s_nop 1
	v_addc_co_u32_e32 v13, vcc, 0, v11, vcc
	v_add_co_u32_e32 v14, vcc, 0x1a900000, v10
	s_nop 1
	v_addc_co_u32_e32 v15, vcc, 0, v11, vcc
	v_add_co_u32_e32 v16, vcc, 0x1aa00000, v10
	s_nop 1
	v_addc_co_u32_e32 v17, vcc, 0, v11, vcc
	v_add_co_u32_e32 v10, vcc, 0x1ab00000, v10
	s_nop 1
	v_addc_co_u32_e32 v11, vcc, 0, v11, vcc
	s_nop 0
	global_load_dword v242, v[12:13], off
	s_nop 0
	global_load_dword v244, v[14:15], off
	s_nop 0
	global_load_dword v243, v[16:17], off
	s_nop 0
	global_load_dword v245, v[10:11], off
	s_add_u32 s0, s0, 64
	s_addc_u32 s1, s1, 0
	v_lshl_add_u64 v[10:11], v[4:5], 0, s[0:1]
	v_add_co_u32_e32 v12, vcc, 0x1a800000, v10
	s_nop 1
	v_addc_co_u32_e32 v13, vcc, 0, v11, vcc
	v_add_co_u32_e32 v14, vcc, 0x1a900000, v10
	s_nop 1
	v_addc_co_u32_e32 v15, vcc, 0, v11, vcc
	v_add_co_u32_e32 v16, vcc, 0x1aa00000, v10
	s_nop 1
	v_addc_co_u32_e32 v17, vcc, 0, v11, vcc
	v_add_co_u32_e32 v10, vcc, 0x1ab00000, v10
	s_nop 1
	v_addc_co_u32_e32 v11, vcc, 0, v11, vcc
	s_nop 0
	global_load_dword v246, v[12:13], off
	s_nop 0
	global_load_dword v248, v[14:15], off
	s_nop 0
	global_load_dword v247, v[16:17], off
	s_nop 0
	global_load_dword v249, v[10:11], off
	s_add_u32 s0, s0, 64
	s_addc_u32 s1, s1, 0
	v_lshl_add_u64 v[10:11], v[4:5], 0, s[0:1]
	v_add_co_u32_e32 v12, vcc, 0x1a800000, v10
	s_nop 1
	v_addc_co_u32_e32 v13, vcc, 0, v11, vcc
	v_add_co_u32_e32 v14, vcc, 0x1a900000, v10
	s_nop 1
	v_addc_co_u32_e32 v15, vcc, 0, v11, vcc
	v_add_co_u32_e32 v16, vcc, 0x1aa00000, v10
	s_nop 1
	v_addc_co_u32_e32 v17, vcc, 0, v11, vcc
	v_add_co_u32_e32 v10, vcc, 0x1ab00000, v10
	s_nop 1
	v_addc_co_u32_e32 v11, vcc, 0, v11, vcc
	s_nop 0
	global_load_dword v250, v[12:13], off
	s_nop 0
	global_load_dword v252, v[14:15], off
	s_nop 0
	global_load_dword v251, v[16:17], off
	s_nop 0
	global_load_dword v253, v[10:11], off
	s_waitcnt vmcnt(0)
; __device__ __forceinline__ float fexp2(float x) { return __builtin_amdgcn_exp2f(x); }
; __device__ __forceinline__ float flog2(float x) { return __builtin_amdgcn_logf(x); }
; __device__ __forceinline__ float log_sigmoid_acc(float x) {
;   return -(fmaxf(-x, 0.f) + flog2(1.f + fexp2(-fabsf(x) * LOG2E)) * 0.6931471805599453f);
; }
; template <bool FOX>
; __device__ __forceinline__ void attn_pair(const Params& p, int it, char* smem, const int wv) {
;     ...
;       if (s_ < n) { const float* fp = Fl + (long)s_ * 16;
;         lf = log_sigmoid_acc(((fp[0] + fp[(long)NTOK * 16]) + (fp[(long)2 * NTOK * 16] + fp[(long)3 * NTOK * 16])) + bf); }
;       run += lf; Fs[s_] = lf;
	v_pk_add_f32 v[10:11], v[222:223], v[224:225]
	s_nop 0
	v_add_f32_e32 v9, v10, v11
	v_add_f32_e32 v9, v7, v9
	v_mul_f32_e64 v10, |v9|, s24
	v_exp_f32_e32 v10, v10
	v_max_f32_e64 v9, -v9, 0
	v_add_f32_e32 v10, 1.0, v10
	v_log_f32_e32 v10, v10
	s_nop 0
	v_fmac_f32_e32 v9, 0x3f317218, v10
	v_xor_b32_e32 v9, 0x80000000, v9
	v_cmp_gt_i32_e32 vcc, s33, v2
	s_nop 1
	v_cndmask_b32_e32 v9, 0, v9, vcc
	v_add_f32_e32 v3, v3, v9
	ds_write_b32 v8, v9
	v_add_u32_e32 v8, 4, v8
	v_add_u32_e32 v2, 1, v2
	v_pk_add_f32 v[10:11], v[226:227], v[228:229]
	s_nop 0
	v_add_f32_e32 v9, v10, v11
	v_add_f32_e32 v9, v7, v9
	v_mul_f32_e64 v10, |v9|, s24
	v_exp_f32_e32 v10, v10
	v_max_f32_e64 v9, -v9, 0
	v_add_f32_e32 v10, 1.0, v10
	v_log_f32_e32 v10, v10
	s_nop 0
	v_fmac_f32_e32 v9, 0x3f317218, v10
	v_xor_b32_e32 v9, 0x80000000, v9
	v_cmp_gt_i32_e32 vcc, s33, v2
	s_nop 1
	v_cndmask_b32_e32 v9, 0, v9, vcc
	v_add_f32_e32 v3, v3, v9
	ds_write_b32 v8, v9
	v_add_u32_e32 v8, 4, v8
	v_add_u32_e32 v2, 1, v2
	v_pk_add_f32 v[10:11], v[230:231], v[232:233]
	s_nop 0
	v_add_f32_e32 v9, v10, v11
	v_add_f32_e32 v9, v7, v9
	v_mul_f32_e64 v10, |v9|, s24
	v_exp_f32_e32 v10, v10
	v_max_f32_e64 v9, -v9, 0
	v_add_f32_e32 v10, 1.0, v10
	v_log_f32_e32 v10, v10
	s_nop 0
	v_fmac_f32_e32 v9, 0x3f317218, v10
	v_xor_b32_e32 v9, 0x80000000, v9
	v_cmp_gt_i32_e32 vcc, s33, v2
	s_nop 1
	v_cndmask_b32_e32 v9, 0, v9, vcc
	v_add_f32_e32 v3, v3, v9
	ds_write_b32 v8, v9
	v_add_u32_e32 v8, 4, v8
	v_add_u32_e32 v2, 1, v2
	v_pk_add_f32 v[10:11], v[234:235], v[236:237]
	s_nop 0
	v_add_f32_e32 v9, v10, v11
	v_add_f32_e32 v9, v7, v9
	v_mul_f32_e64 v10, |v9|, s24
	v_exp_f32_e32 v10, v10
	v_max_f32_e64 v9, -v9, 0
	v_add_f32_e32 v10, 1.0, v10
	v_log_f32_e32 v10, v10
	s_nop 0
	v_fmac_f32_e32 v9, 0x3f317218, v10
	v_xor_b32_e32 v9, 0x80000000, v9
	v_cmp_gt_i32_e32 vcc, s33, v2
	s_nop 1
	v_cndmask_b32_e32 v9, 0, v9, vcc
	v_add_f32_e32 v3, v3, v9
	ds_write_b32 v8, v9
	v_add_u32_e32 v8, 4, v8
	v_add_u32_e32 v2, 1, v2
	v_pk_add_f32 v[10:11], v[238:239], v[240:241]
	s_nop 0
	v_add_f32_e32 v9, v10, v11
	v_add_f32_e32 v9, v7, v9
	v_mul_f32_e64 v10, |v9|, s24
	v_exp_f32_e32 v10, v10
	v_max_f32_e64 v9, -v9, 0
	v_add_f32_e32 v10, 1.0, v10
	v_log_f32_e32 v10, v10
	s_nop 0
	v_fmac_f32_e32 v9, 0x3f317218, v10
	v_xor_b32_e32 v9, 0x80000000, v9
	v_cmp_gt_i32_e32 vcc, s33, v2
	s_nop 1
	v_cndmask_b32_e32 v9, 0, v9, vcc
	v_add_f32_e32 v3, v3, v9
	ds_write_b32 v8, v9
	v_add_u32_e32 v8, 4, v8
	v_add_u32_e32 v2, 1, v2
	v_pk_add_f32 v[10:11], v[242:243], v[244:245]
	s_nop 0
	v_add_f32_e32 v9, v10, v11
	v_add_f32_e32 v9, v7, v9
	v_mul_f32_e64 v10, |v9|, s24
	v_exp_f32_e32 v10, v10
	v_max_f32_e64 v9, -v9, 0
	v_add_f32_e32 v10, 1.0, v10
	v_log_f32_e32 v10, v10
	s_nop 0
	v_fmac_f32_e32 v9, 0x3f317218, v10
	v_xor_b32_e32 v9, 0x80000000, v9
	v_cmp_gt_i32_e32 vcc, s33, v2
	s_nop 1
	v_cndmask_b32_e32 v9, 0, v9, vcc
	v_add_f32_e32 v3, v3, v9
	ds_write_b32 v8, v9
	v_add_u32_e32 v8, 4, v8
	v_add_u32_e32 v2, 1, v2
	v_pk_add_f32 v[10:11], v[246:247], v[248:249]
	s_nop 0
	v_add_f32_e32 v9, v10, v11
	v_add_f32_e32 v9, v7, v9
	v_mul_f32_e64 v10, |v9|, s24
	v_exp_f32_e32 v10, v10
	v_max_f32_e64 v9, -v9, 0
	v_add_f32_e32 v10, 1.0, v10
	v_log_f32_e32 v10, v10
	s_nop 0
	v_fmac_f32_e32 v9, 0x3f317218, v10
	v_xor_b32_e32 v9, 0x80000000, v9
	v_cmp_gt_i32_e32 vcc, s33, v2
	s_nop 1
	v_cndmask_b32_e32 v9, 0, v9, vcc
	v_add_f32_e32 v3, v3, v9
	ds_write_b32 v8, v9
	v_add_u32_e32 v8, 4, v8
	v_add_u32_e32 v2, 1, v2
	v_pk_add_f32 v[10:11], v[250:251], v[252:253]
	s_nop 0
	v_add_f32_e32 v9, v10, v11
	v_add_f32_e32 v9, v7, v9
	v_mul_f32_e64 v10, |v9|, s24
	v_exp_f32_e32 v10, v10
	v_max_f32_e64 v9, -v9, 0
	v_add_f32_e32 v10, 1.0, v10
	v_log_f32_e32 v10, v10
	s_nop 0
	v_fmac_f32_e32 v9, 0x3f317218, v10
	v_xor_b32_e32 v9, 0x80000000, v9
	v_cmp_gt_i32_e32 vcc, s33, v2
	s_nop 1
	v_cndmask_b32_e32 v9, 0, v9, vcc
	v_add_f32_e32 v3, v3, v9
	ds_write_b32 v8, v9
	v_add_u32_e32 v8, 4, v8
	v_add_u32_e32 v2, 1, v2
